# v24 + attention ping copy QK section: fragment reads prefetched one step ahead (softmax VALU kept in original slots)
# baseline (speedup 1.0000x reference)
; __device__ __forceinline__ void finishSM(f32x16& p0, f32x16& p1, float alpha, float& l_reg, bf16x8& pa0, bf16x8& pa1, bf16x8& pa2, bf16x8& pa3) {
; #pragma unroll
;     for (int r = 0; r < 16; ++r) p1[r] = __builtin_amdgcn_exp2f(p1[r]);
;     float ps = 0;
; #pragma unroll
;     for (int r = 0; r < 16; ++r) ps += p0[r];
; #pragma unroll
;     for (int r = 0; r < 16; ++r) ps += p1[r];
;     { auto rr = __builtin_amdgcn_permlane32_swap(__float_as_uint(ps), __float_as_uint(ps), false, false); ps = __uint_as_float(rr[0]) + __uint_as_float(rr[1]); }
;     l_reg = l_reg * alpha + ps;
;     ...
;     PK4(p0, 0, pa0); PK4(p0, 8, pa1); PK4(p1, 0, pa2); PK4(p1, 8, pa3);
;     ...
; }
; __device__ __forceinline__ void qkt(f32x16& p0, f32x16& p1, const char* Ks, const bf16x8* qr, const char* qrl, int r32, int hi) {
;     p0 = f32x16{}; p1 = f32x16{};
; #pragma unroll
;     for (int d0 = 0; d0 < 12; ++d0) { const int cb = (d0 * 16 + hi * 8) * 2;
;         const bf16x8 b0 = *reinterpret_cast<const bf16x8*>(Ks + KSWZ(r32, cb));
;         const bf16x8 b1 = *reinterpret_cast<const bf16x8*>(Ks + KSWZ(32 + r32, cb));
;         const bf16x8 qq = d0 < QREG ? qr[d0 < QREG ? d0 : 0] : *reinterpret_cast<const bf16x8*>(qrl + (d0 - QREG) * 1024);
;         p0 = __builtin_amdgcn_mfma_f32_32x32x16_bf16(b0, qq, p0, 0, 0, 0);
;         p1 = __builtin_amdgcn_mfma_f32_32x32x16_bf16(b1, qq, p1, 0, 0, 0); }
.LBB0_1380:
	v_add_u32_e32 v68, s14, v183
	ds_read_b128 v[64:67], v68
	ds_read_b128 v[68:71], v68 offset:16384
	v_add_u32_e32 v224, s14, v185
	ds_read_b128 v[220:223], v224
	ds_read_b128 v[224:227], v224 offset:16384
	v_add_f32_e32 v140, 0, v136
	s_waitcnt lgkmcnt(3)
	v_mfma_f32_32x32x16_bf16 v[80:95], v[64:67], v[116:119], 0
	v_add_f32_e32 v140, v166, v140
	v_add_f32_e32 v140, v137, v140
	v_add_f32_e32 v140, v167, v140
	v_add_f32_e32 v140, v138, v140
	v_add_f32_e32 v140, v168, v140
	v_add_f32_e32 v140, v139, v140
	v_add_f32_e32 v140, v165, v140
	s_waitcnt lgkmcnt(2)
	v_mfma_f32_32x32x16_bf16 v[64:79], v[68:71], v[116:119], 0
	v_add_f32_e32 v140, v144, v140
	v_add_f32_e32 v140, v146, v140
	v_add_f32_e32 v140, v145, v140
	v_add_f32_e32 v140, v164, v140
	v_exp_f32_e32 v132, v132
	v_add_f32_e32 v140, v141, v140
	v_exp_f32_e32 v133, v133
	v_add_u32_e32 v232, s14, v187
	ds_read_b128 v[228:231], v232
	ds_read_b128 v[232:235], v232 offset:16384
	s_waitcnt lgkmcnt(3)
	v_mfma_f32_32x32x16_bf16 v[80:95], v[220:223], v[112:115], v[80:95]
	v_add_f32_e32 v140, v143, v140
	v_exp_f32_e32 v134, v134
	v_add_f32_e32 v140, v142, v140
	v_exp_f32_e32 v135, v135
	v_add_f32_e32 v140, v147, v140
	s_waitcnt lgkmcnt(2)
	v_mfma_f32_32x32x16_bf16 v[64:79], v[224:227], v[112:115], v[64:79]
	v_exp_f32_e32 v122, v122
	v_add_f32_e32 v140, v132, v140
	v_exp_f32_e32 v123, v123
	v_add_f32_e32 v140, v133, v140
	v_exp_f32_e32 v124, v124
	v_add_f32_e32 v140, v134, v140
	v_add_u32_e32 v224, s14, v189
	ds_read_b128 v[220:223], v224
	ds_read_b128 v[224:227], v224 offset:16384
	s_waitcnt lgkmcnt(3)
	v_mfma_f32_32x32x16_bf16 v[80:95], v[228:231], v[108:111], v[80:95]
	v_exp_f32_e32 v125, v125
	v_add_f32_e32 v140, v135, v140
	v_exp_f32_e32 v126, v126
	v_add_f32_e32 v140, v122, v140
	v_exp_f32_e32 v127, v127
	v_add_f32_e32 v140, v123, v140
	v_exp_f32_e32 v130, v130
	s_waitcnt lgkmcnt(2)
	v_mfma_f32_32x32x16_bf16 v[64:79], v[232:235], v[108:111], v[64:79]
	v_add_f32_e32 v140, v124, v140
	v_exp_f32_e32 v131, v131
	v_add_f32_e32 v140, v125, v140
	v_exp_f32_e32 v120, v120
	v_add_f32_e32 v140, v126, v140
	v_exp_f32_e32 v121, v121
	v_add_u32_e32 v232, s14, v191
	ds_read_b128 v[228:231], v232
	ds_read_b128 v[232:235], v232 offset:16384
	s_waitcnt lgkmcnt(3)
	v_mfma_f32_32x32x16_bf16 v[80:95], v[220:223], v[104:107], v[80:95]
	v_add_f32_e32 v140, v127, v140
	v_exp_f32_e32 v128, v128
	v_add_f32_e32 v140, v130, v140
	v_exp_f32_e32 v129, v129
	v_add_f32_e32 v140, v131, v140
	s_waitcnt lgkmcnt(2)
	v_mfma_f32_32x32x16_bf16 v[64:79], v[224:227], v[104:107], v[64:79]
	v_add_f32_e32 v140, v120, v140
	v_add_f32_e32 v140, v121, v140
	v_add_f32_e32 v140, v128, v140
	v_add_u32_e32 v224, s14, v193
	ds_read_b128 v[220:223], v224
	ds_read_b128 v[224:227], v224 offset:16384
	s_waitcnt lgkmcnt(3)
	v_mfma_f32_32x32x16_bf16 v[80:95], v[228:231], v[100:103], v[80:95]
	s_waitcnt lgkmcnt(2)
	v_mfma_f32_32x32x16_bf16 v[64:79], v[232:235], v[100:103], v[64:79]
	ds_read_b128 v[240:243], v177
	v_add_u32_e32 v236, s14, v195
	ds_read_b128 v[232:235], v236
	ds_read_b128 v[236:239], v236 offset:16384
	s_waitcnt lgkmcnt(4)
	v_mfma_f32_32x32x16_bf16 v[80:95], v[220:223], v[96:99], v[80:95]
	s_waitcnt lgkmcnt(3)
	v_mfma_f32_32x32x16_bf16 v[64:79], v[224:227], v[96:99], v[64:79]
	ds_read_b128 v[228:231], v177 offset:1024
	v_add_u32_e32 v224, s14, v197
	ds_read_b128 v[220:223], v224
	ds_read_b128 v[224:227], v224 offset:16384
	s_waitcnt lgkmcnt(4)
	v_mfma_f32_32x32x16_bf16 v[80:95], v[232:235], v[240:243], v[80:95]
	s_waitcnt lgkmcnt(3)
	v_mfma_f32_32x32x16_bf16 v[64:79], v[236:239], v[240:243], v[64:79]
	ds_read_b128 v[240:243], v177 offset:2048
	v_add_u32_e32 v236, s14, v199
	ds_read_b128 v[232:235], v236
	ds_read_b128 v[236:239], v236 offset:16384
	s_waitcnt lgkmcnt(4)
	v_mfma_f32_32x32x16_bf16 v[80:95], v[220:223], v[228:231], v[80:95]
	s_waitcnt lgkmcnt(3)
	v_mfma_f32_32x32x16_bf16 v[64:79], v[224:227], v[228:231], v[64:79]
	ds_read_b128 v[228:231], v177 offset:3072
	v_add_u32_e32 v224, s14, v201
	ds_read_b128 v[220:223], v224
	ds_read_b128 v[224:227], v224 offset:16384
	s_waitcnt lgkmcnt(4)
	v_mfma_f32_32x32x16_bf16 v[80:95], v[232:235], v[240:243], v[80:95]
	s_waitcnt lgkmcnt(3)
	v_mfma_f32_32x32x16_bf16 v[64:79], v[236:239], v[240:243], v[64:79]
	ds_read_b128 v[240:243], v177 offset:4096
	v_add_u32_e32 v236, s14, v203
	ds_read_b128 v[232:235], v236
	ds_read_b128 v[236:239], v236 offset:16384
	s_waitcnt lgkmcnt(4)
	v_mfma_f32_32x32x16_bf16 v[80:95], v[220:223], v[228:231], v[80:95]
	s_waitcnt lgkmcnt(3)
	v_mfma_f32_32x32x16_bf16 v[64:79], v[224:227], v[228:231], v[64:79]
	ds_read_b128 v[228:231], v177 offset:5120
	v_add_u32_e32 v224, s14, v205
	ds_read_b128 v[220:223], v224
	ds_read_b128 v[224:227], v224 offset:16384
	s_waitcnt lgkmcnt(4)
	v_mfma_f32_32x32x16_bf16 v[80:95], v[232:235], v[240:243], v[80:95]
	s_waitcnt lgkmcnt(3)
	v_mfma_f32_32x32x16_bf16 v[64:79], v[236:239], v[240:243], v[64:79]
	v_cvt_pk_bf16_f32 v136, v136, v166
	v_cvt_pk_bf16_f32 v137, v137, v167
	v_cvt_pk_bf16_f32 v138, v138, v168
	v_cvt_pk_bf16_f32 v139, v139, v165
	v_cvt_pk_bf16_f32 v144, v144, v146
	v_cvt_pk_bf16_f32 v145, v145, v164
	s_waitcnt lgkmcnt(1)
	v_mfma_f32_32x32x16_bf16 v[80:95], v[220:223], v[228:231], v[80:95]
	v_add_f32_e32 v232, v129, v140
	v_mov_b32_e32 v233, v232
	v_cvt_pk_bf16_f32 v146, v141, v143
	v_cvt_pk_bf16_f32 v147, v142, v147
	v_cvt_pk_bf16_f32 v234, v132, v133
	v_cvt_pk_bf16_f32 v235, v134, v135
	s_nop 1
	v_permlane32_swap_b32_e32 v232, v233
	s_waitcnt lgkmcnt(0)
; __device__ __forceinline__ void finishSM(f32x16& p0, f32x16& p1, float alpha, float& l_reg, bf16x8& pa0, bf16x8& pa1, bf16x8& pa2, bf16x8& pa3) {
; #pragma unroll
;     for (int r = 0; r < 16; ++r) p1[r] = __builtin_amdgcn_exp2f(p1[r]);
;     float ps = 0;
; #pragma unroll
;     for (int r = 0; r < 16; ++r) ps += p0[r];
; #pragma unroll
;     for (int r = 0; r < 16; ++r) ps += p1[r];
;     { auto rr = __builtin_amdgcn_permlane32_swap(__float_as_uint(ps), __float_as_uint(ps), false, false); ps = __uint_as_float(rr[0]) + __uint_as_float(rr[1]); }
;     l_reg = l_reg * alpha + ps;
;     ...
;     PK4(p0, 0, pa0); PK4(p0, 8, pa1); PK4(p1, 0, pa2); PK4(p1, 8, pa3);
;     ...
; }
; __device__ __forceinline__ void qkt(f32x16& p0, f32x16& p1, const char* Ks, const bf16x8* qr, const char* qrl, int r32, int hi) {
;     p0 = f32x16{}; p1 = f32x16{};
; #pragma unroll
;     for (int d0 = 0; d0 < 12; ++d0) { const int cb = (d0 * 16 + hi * 8) * 2;
;         const bf16x8 b0 = *reinterpret_cast<const bf16x8*>(Ks + KSWZ(r32, cb));
;         const bf16x8 b1 = *reinterpret_cast<const bf16x8*>(Ks + KSWZ(32 + r32, cb));
;         const bf16x8 qq = d0 < QREG ? qr[d0 < QREG ? d0 : 0] : *reinterpret_cast<const bf16x8*>(qrl + (d0 - QREG) * 1024);
;         p0 = __builtin_amdgcn_mfma_f32_32x32x16_bf16(b0, qq, p0, 0, 0, 0);
;         p1 = __builtin_amdgcn_mfma_f32_32x32x16_bf16(b1, qq, p1, 0, 0, 0); }
; }
; __device__ __forceinline__ int v_st(int k, int c) { const int kk = (k & ~0xC) | ((k & 4) << 1) | ((k & 8) >> 1); return ((kk >> 3) * 4 + (c >> 5)) * 512 + ((kk & 7) * 32 + (c & 31)) * 2; }
; __device__ __forceinline__ int v_rd_base(int lane) { return ((lane & 3) << 3) | (((lane >> 2) & 3) << 6) | (((lane >> 4) & 1) << 5) | (((lane >> 5) & 1) << 8); }
; template <int OFF> __device__ __forceinline__ s16x4 tr_read(int vb) { s16x4 r; asm volatile("ds_read_b64_tr_b16 %0, %1 offset:%2" : "=&v"(r) : "v"(vb), "i"(OFF) : "memory"); return r; }
; template <int D0> __device__ __forceinline__ void pv_one(f32x16& od, int vb, bf16x8 pa0, bf16x8 pa1, bf16x8 pa2, bf16x8 pa3) {
;     const s16x4 l0 = tr_read<v_rd_off(D0, 0, 0)>(vb), h0 = tr_read<v_rd_off(D0, 0, 1)>(vb), l1 = tr_read<v_rd_off(D0, 1, 0)>(vb), h1 = tr_read<v_rd_off(D0, 1, 1)>(vb);
;     const s16x4 l2 = tr_read<v_rd_off(D0, 2, 0)>(vb), h2 = tr_read<v_rd_off(D0, 2, 1)>(vb), l3 = tr_read<v_rd_off(D0, 3, 0)>(vb), h3 = tr_read<v_rd_off(D0, 3, 1)>(vb);
	v_mfma_f32_32x32x16_bf16 v[64:79], v[224:227], v[228:231], v[64:79]
	v_cvt_pk_bf16_f32 v236, v122, v123
	v_permlane32_swap_b32_e32 v136, v138
	v_cvt_pk_bf16_f32 v237, v124, v125
	v_permlane32_swap_b32_e32 v234, v236
	v_cvt_pk_bf16_f32 v238, v126, v127
	v_cvt_pk_bf16_f32 v239, v130, v131
	v_cvt_pk_bf16_f32 v240, v120, v121
	v_cvt_pk_bf16_f32 v241, v128, v129
	v_permlane32_swap_b32_e32 v137, v139
	v_permlane32_swap_b32_e32 v144, v146
	v_permlane32_swap_b32_e32 v145, v147
	v_permlane32_swap_b32_e32 v235, v237
	v_permlane32_swap_b32_e32 v238, v240
	v_permlane32_swap_b32_e32 v239, v241
	v_lshl_add_u64 v[164:165], s[68:69], 0, v[156:157]
	s_mov_b32 s4, 0x23480000
	v_add_co_u32_e32 v120, vcc, s4, v164
	s_mov_b32 s4, 0x234a0000
	s_nop 0
	v_addc_co_u32_e32 v121, vcc, 0, v165, vcc
	v_add_co_u32_e32 v124, vcc, s4, v164
	v_lshl_add_u64 v[166:167], s[68:69], 0, v[154:155]
	s_nop 0
	v_addc_co_u32_e32 v125, vcc, 0, v165, vcc
	v_add_co_u32_e32 v128, vcc, s97, v166
	v_lshl_add_u64 v[168:169], s[68:69], 0, v[152:153]
	s_nop 0
	v_addc_co_u32_e32 v129, vcc, 0, v167, vcc
	v_add_co_u32_e32 v132, vcc, s97, v168
	v_lshl_add_u64 v[170:171], s[68:69], 0, v[150:151]
	s_nop 0
	v_addc_co_u32_e32 v133, vcc, 0, v169, vcc
	v_add_co_u32_e32 v140, vcc, s97, v170
	global_load_dwordx4 v[120:123], v[120:121], off
	s_nop 0
	global_load_dwordx4 v[124:127], v[124:125], off
	s_nop 0
	global_load_dwordx4 v[128:131], v[128:129], off
	s_nop 0
	global_load_dwordx4 v[132:135], v[132:133], off
	v_addc_co_u32_e32 v141, vcc, 0, v171, vcc
	global_load_dwordx4 v[140:143], v[140:141], off
	ds_read_b64_tr_b16 v[242:243], v176 offset:0
	ds_read_b64_tr_b16 v[244:245], v176 offset:0x800
	ds_read_b64_tr_b16 v[246:247], v176 offset:0x1000
	ds_read_b64_tr_b16 v[248:249], v176 offset:0x1800
	ds_read_b64_tr_b16 v[250:251], v176 offset:0x2000
	ds_read_b64_tr_b16 v[252:253], v176 offset:0x2800
	ds_read_b64_tr_b16 v[208:209], v176 offset:0x3000
	ds_read_b64_tr_b16 v[210:211], v176 offset:0x3800
	s_waitcnt lgkmcnt(0)
	s_nop 0
	v_mfma_f32_32x32x16_bf16 v[0:15], v[136:139], v[242:245], v[0:15]
	v_mfma_f32_32x32x16_bf16 v[0:15], v[144:147], v[246:249], v[0:15]
	v_mfma_f32_32x32x16_bf16 v[0:15], v[234:237], v[250:253], v[0:15]
	v_mfma_f32_32x32x16_bf16 v[0:15], v[238:241], v[208:211], v[0:15]
	ds_read_b64_tr_b16 v[208:209], v176 offset:0x200
	ds_read_b64_tr_b16 v[210:211], v176 offset:0xa00
	ds_read_b64_tr_b16 v[242:243], v176 offset:0x1200
	ds_read_b64_tr_b16 v[244:245], v176 offset:0x1a00
	ds_read_b64_tr_b16 v[246:247], v176 offset:0x2200
	ds_read_b64_tr_b16 v[248:249], v176 offset:0x2a00
	ds_read_b64_tr_b16 v[250:251], v176 offset:0x3200
	ds_read_b64_tr_b16 v[252:253], v176 offset:0x3a00
	s_waitcnt lgkmcnt(0)
	s_nop 0
	v_mfma_f32_32x32x16_bf16 v[48:63], v[136:139], v[208:211], v[48:63]
	ds_read_b64_tr_b16 v[208:209], v176 offset:0x400
	ds_read_b64_tr_b16 v[210:211], v176 offset:0xc00
	v_mfma_f32_32x32x16_bf16 v[48:63], v[144:147], v[242:245], v[48:63]
	ds_read_b64_tr_b16 v[242:243], v176 offset:0x1400
	ds_read_b64_tr_b16 v[244:245], v176 offset:0x1c00
	v_mfma_f32_32x32x16_bf16 v[48:63], v[234:237], v[246:249], v[48:63]
	ds_read_b64_tr_b16 v[246:247], v176 offset:0x2400
	ds_read_b64_tr_b16 v[248:249], v176 offset:0x2c00
	v_mfma_f32_32x32x16_bf16 v[48:63], v[238:241], v[250:253], v[48:63]
	ds_read_b64_tr_b16 v[250:251], v176 offset:0x3400
	ds_read_b64_tr_b16 v[252:253], v176 offset:0x3c00
	s_waitcnt lgkmcnt(0)
	v_mfma_f32_32x32x16_bf16 v[32:47], v[136:139], v[208:211], v[32:47]
	ds_read_b64_tr_b16 v[208:209], v176 offset:0x600
	ds_read_b64_tr_b16 v[210:211], v176 offset:0xe00
	v_mfma_f32_32x32x16_bf16 v[32:47], v[144:147], v[242:245], v[32:47]
	ds_read_b64_tr_b16 v[242:243], v176 offset:0x1600
	ds_read_b64_tr_b16 v[244:245], v176 offset:0x1e00
	v_mfma_f32_32x32x16_bf16 v[32:47], v[234:237], v[246:249], v[32:47]
	ds_read_b64_tr_b16 v[246:247], v176 offset:0x2600
	ds_read_b64_tr_b16 v[248:249], v176 offset:0x2e00
	v_mfma_f32_32x32x16_bf16 v[32:47], v[238:241], v[250:253], v[32:47]
	ds_read_b64_tr_b16 v[250:251], v176 offset:0x3600
	ds_read_b64_tr_b16 v[252:253], v176 offset:0x3e00
	s_waitcnt lgkmcnt(0)
	v_mfma_f32_32x32x16_bf16 v[16:31], v[136:139], v[208:211], v[16:31]
	v_max_f32_e32 v136, v81, v81
	v_max_f32_e32 v137, v80, v80
	v_max_f32_e32 v136, v137, v136
	v_max3_f32 v136, v136, v82, v83
	v_max3_f32 v136, v136, v84, v85
	v_max3_f32 v136, v136, v86, v87
	v_max3_f32 v136, v136, v88, v89
	v_max3_f32 v136, v136, v90, v91
	v_mfma_f32_32x32x16_bf16 v[16:31], v[144:147], v[242:245], v[16:31]
	v_max3_f32 v136, v136, v92, v93
	v_max3_f32 v136, v136, v94, v95
	v_max3_f32 v136, v136, v64, v65
	v_max3_f32 v136, v136, v66, v67
	v_max3_f32 v136, v136, v68, v69
	v_max3_f32 v136, v136, v70, v71
	v_max3_f32 v136, v136, v72, v73
	v_max3_f32 v136, v136, v74, v75
	v_mfma_f32_32x32x16_bf16 v[16:31], v[234:237], v[246:249], v[16:31]
	v_max3_f32 v136, v136, v76, v77
	v_max3_f32 v136, v136, v78, v79
	v_mov_b32_e32 v137, v136
	s_nop 1
	v_permlane32_swap_b32_e32 v136, v137
	v_max_f32_e32 v137, v137, v137
	v_max_f32_e32 v136, v136, v136
	v_max_f32_e32 v136, v136, v137
	v_sub_f32_e32 v137, v136, v158
	v_cmp_ge_f32_e32 vcc, s62, v137
	v_max_f32_e32 v137, v158, v158
	v_mfma_f32_32x32x16_bf16 v[16:31], v[238:241], v[250:253], v[16:31]
	v_max_f32_e32 v136, v137, v136
	v_sub_f32_e32 v137, v158, v136
	v_exp_f32_e32 v137, v137
	s_cmp_eq_u64 vcc, exec
	s_cselect_b64 s[4:5], -1, 0
	s_barrier
; #define SWRITE(b) do { *(bf16x8*)(V_lds + (b) * SHM_V + vst0) = vs0; *(bf16x8*)(V_lds + (b) * SHM_V + vst1) = vs1; \
;     *(bf16x8*)(K_lds + (b) * SHM_K + KSWZ(kr0, kc0 * 16)) = ks0; *(bf16x8*)(K_lds + (b) * SHM_K + KSWZ(kr1, kc1 * 16)) = ks1; *(bf16x8*)(K_lds + (b) * SHM_K + KSWZ(kr2, kc2 * 16)) = ks2; } while (0)
; #define SWAIT() asm volatile("s_waitcnt vmcnt(0)" ::: "memory")
; #define RESC(a) do { if (__any((a) < 1.f)) { if (hi == 0) al_l[r32] = (a); asm volatile("s_waitcnt lgkmcnt(0)" ::: "memory"); \
;     _Pragma("unroll") for (int d = 0; d < 4; ++d) _Pragma("unroll") for (int r = 0; r < 16; ++r) o[d][r] *= al_l[crow(r, hi)]; } } while (0)
; __device__ __forceinline__ void attn_unit(const bf16_t* __restrict__ Qb, const bf16_t* __restrict__ Kh, const bf16_t* __restrict__ Vh, bf16_t* __restrict__ Ob, int seq, char* lds) {
;     ...
;         __syncthreads(); SWAIT(); SWRITE(1);
;         RESC(alA); __syncthreads();
	s_waitcnt vmcnt(0)
	v_cndmask_b32_e64 v234, v137, 1.0, s[4:5]
	v_cmp_gt_f32_e32 vcc, 1.0, v234
	s_waitcnt vmcnt(4)
	ds_write_b128 v178, v[120:123]
	s_waitcnt vmcnt(3)
	ds_write_b128 v179, v[124:127]
	s_waitcnt vmcnt(2)
	ds_write_b128 v180, v[128:131] offset:32768
	s_waitcnt vmcnt(1)
	ds_write_b128 v181, v[132:135] offset:32768
	s_waitcnt vmcnt(0)
	ds_write_b128 v182, v[140:143] offset:32768
	s_cbranch_vccz .LBB0_1384
	s_and_saveexec_b64 s[12:13], s[2:3]
	ds_write_b32 v173, v234 offset:128
	s_or_b64 exec, exec, s[12:13]
	s_waitcnt lgkmcnt(0)
	v_add_u32_e32 v132, v149, v160
	ds_read_b128 v[120:123], v132 offset:224
	ds_read_b128 v[124:127], v132 offset:192
	ds_read_b128 v[128:131], v132 offset:160
	ds_read_b128 v[132:135], v132 offset:128
	s_waitcnt lgkmcnt(3)
	v_pk_mul_f32 v[12:13], v[12:13], v[120:121]
	s_waitcnt lgkmcnt(2)
	v_pk_mul_f32 v[8:9], v[8:9], v[124:125]
	s_waitcnt lgkmcnt(1)
	v_pk_mul_f32 v[4:5], v[4:5], v[128:129]
	v_pk_mul_f32 v[14:15], v[14:15], v[122:123]
	v_pk_mul_f32 v[10:11], v[10:11], v[126:127]
	v_pk_mul_f32 v[6:7], v[6:7], v[130:131]
	s_waitcnt lgkmcnt(0)
	v_pk_mul_f32 v[2:3], v[2:3], v[134:135]
	v_pk_mul_f32 v[0:1], v[0:1], v[132:133]
	v_pk_mul_f32 v[60:61], v[60:61], v[120:121]
	v_pk_mul_f32 v[56:57], v[56:57], v[124:125]
	v_pk_mul_f32 v[52:53], v[52:53], v[128:129]
	v_pk_mul_f32 v[62:63], v[62:63], v[122:123]
	v_pk_mul_f32 v[58:59], v[58:59], v[126:127]
	v_pk_mul_f32 v[54:55], v[54:55], v[130:131]
	v_pk_mul_f32 v[50:51], v[50:51], v[134:135]
	v_pk_mul_f32 v[48:49], v[48:49], v[132:133]
	v_pk_mul_f32 v[44:45], v[44:45], v[120:121]
	v_pk_mul_f32 v[40:41], v[40:41], v[124:125]
	v_pk_mul_f32 v[36:37], v[36:37], v[128:129]
	v_pk_mul_f32 v[46:47], v[46:47], v[122:123]
	v_pk_mul_f32 v[42:43], v[42:43], v[126:127]
	v_pk_mul_f32 v[38:39], v[38:39], v[130:131]
	v_pk_mul_f32 v[34:35], v[34:35], v[134:135]
	v_pk_mul_f32 v[32:33], v[32:33], v[132:133]
	v_pk_mul_f32 v[28:29], v[28:29], v[120:121]
	v_pk_mul_f32 v[24:25], v[24:25], v[124:125]
	v_pk_mul_f32 v[20:21], v[20:21], v[128:129]
	v_pk_mul_f32 v[30:31], v[30:31], v[122:123]
	v_pk_mul_f32 v[26:27], v[26:27], v[126:127]
	v_pk_mul_f32 v[22:23], v[22:23], v[130:131]
	v_pk_mul_f32 v[18:19], v[18:19], v[134:135]
	v_pk_mul_f32 v[16:17], v[16:17], v[132:133]
